# also: LoRA-entry projection units assigned XCD-aware (three kinds of an M-tile on one XCD)
# speedup vs baseline: 1.0753x; 1.0001x over previous
.LBB0_435:
	s_cmpk_gt_i32 s55, 0x30b
	s_mov_b64 s[0:1], -1
	s_cbranch_scc0 .LBB0_823
	s_add_i32 s0, s55, 0xfffffcf4
	s_add_i32 s1, s0, 4
	s_and_b32 s35, s1, 7
	s_lshr_b32 s1, s1, 3
	s_mul_i32 s0, s35, 24
	s_add_i32 vcc_lo, s0, s1
	s_add_i32 vcc_hi, s35, 0xbc
	s_cmp_lt_u32 s35, 4
	s_cselect_b32 vcc_hi, s0, vcc_hi
	s_cmp_lt_u32 s1, 24
	s_cselect_b32 s0, vcc_lo, vcc_hi
	s_mov_b32 s98, s0
	s_mul_i32 s1, s0, 0xab
	s_bfe_u32 s35, s1, 0x70009
	s_mul_i32 s62, s35, -3
	s_add_i32 s62, s62, s0
	s_add_i32 s74, s62, 3
	s_lshl_b32 s75, s35, 8
	s_cmp_eq_u32 s74, 5
	s_cselect_b64 s[0:1], -1, 0
	s_and_b64 s[4:5], s[0:1], exec
	v_mov_b32_e32 v1, v174
	s_movk_i32 s4, 0x100
	s_cselect_b32 s34, 0x80, 64
	s_nop 0
	v_cmp_gt_i32_e32 vcc, s4, v1
	s_and_saveexec_b64 s[4:5], vcc
	s_xor_b64 s[90:91], exec, s[4:5]
	s_cbranch_execz .LBB0_760
	s_waitcnt lgkmcnt(0)
	s_barrier
	v_and_b32_e32 v2, 0x4f, v1
	v_bfe_u32 v130, v1, 4, 2
	v_and_b32_e32 v140, 0xffffff8f, v1
	v_mul_u32_u24_e32 v133, 0x90, v2
	v_mov_b32_e32 v2, 0
	v_mul_lo_u32 v131, v140, s49
	v_lshlrev_b32_e32 v132, 4, v130
	s_mov_b32 s4, 0
	v_mov_b32_e32 v3, v2
	s_waitcnt vmcnt(0)
	v_mov_b32_e32 v4, v2
	v_mov_b32_e32 v5, v2
	v_mov_b32_e32 v6, v2
	v_mov_b32_e32 v7, v2
	v_mov_b32_e32 v8, v2
	v_mov_b32_e32 v9, v2
	v_mov_b32_e32 v10, v2
	v_mov_b32_e32 v11, v2
	v_mov_b32_e32 v12, v2
	v_mov_b32_e32 v13, v2
	v_mov_b32_e32 v14, v2
	v_mov_b32_e32 v15, v2
	v_mov_b32_e32 v16, v2
	v_mov_b32_e32 v17, v2
	v_mov_b32_e32 v18, v2
	v_mov_b32_e32 v19, v2
	v_mov_b32_e32 v20, v2
	v_mov_b32_e32 v21, v2
	v_mov_b32_e32 v22, v2
	v_mov_b32_e32 v23, v2
	s_waitcnt vmcnt(2)
	v_mov_b32_e32 v24, v2
	v_mov_b32_e32 v25, v2
	v_mov_b32_e32 v26, v2
	v_mov_b32_e32 v27, v2
	s_waitcnt vmcnt(1)
	v_mov_b32_e32 v28, v2
	v_mov_b32_e32 v29, v2
	v_mov_b32_e32 v30, v2
	v_mov_b32_e32 v31, v2
	s_waitcnt vmcnt(0)
	v_mov_b32_e32 v32, v2
	v_mov_b32_e32 v33, v2
	v_mov_b32_e32 v34, v2
	v_mov_b32_e32 v35, v2
	v_mov_b32_e32 v36, v2
	v_mov_b32_e32 v37, v2
	v_mov_b32_e32 v38, v2
	v_mov_b32_e32 v39, v2
	v_mov_b32_e32 v40, v2
	v_mov_b32_e32 v41, v2
	v_mov_b32_e32 v42, v2
	v_mov_b32_e32 v43, v2
	v_mov_b32_e32 v44, v2
	v_mov_b32_e32 v45, v2
	v_mov_b32_e32 v46, v2
	v_mov_b32_e32 v47, v2
	v_mov_b32_e32 v48, v2
	v_mov_b32_e32 v49, v2
	v_mov_b32_e32 v50, v2
	v_mov_b32_e32 v51, v2
	v_mov_b32_e32 v52, v2
	v_mov_b32_e32 v53, v2
	v_mov_b32_e32 v54, v2
	v_mov_b32_e32 v55, v2
	v_mov_b32_e32 v56, v2
	v_mov_b32_e32 v57, v2
	v_mov_b32_e32 v58, v2
	v_mov_b32_e32 v59, v2
	v_mov_b32_e32 v60, v2
	v_mov_b32_e32 v61, v2
	v_mov_b32_e32 v62, v2
	v_mov_b32_e32 v63, v2
	v_mov_b32_e32 v64, v2
	v_mov_b32_e32 v65, v2
	v_mov_b32_e32 v66, v2
	v_mov_b32_e32 v67, v2
	v_mov_b32_e32 v68, v2
	v_mov_b32_e32 v69, v2
	v_mov_b32_e32 v70, v2
	v_mov_b32_e32 v71, v2
	v_mov_b32_e32 v72, v2
	v_mov_b32_e32 v73, v2
	v_mov_b32_e32 v74, v2
	v_mov_b32_e32 v75, v2
	v_mov_b32_e32 v76, v2
	v_mov_b32_e32 v77, v2
	v_mov_b32_e32 v78, v2
	v_mov_b32_e32 v79, v2
	v_mov_b32_e32 v80, v2
	v_mov_b32_e32 v81, v2
	v_mov_b32_e32 v82, v2
	v_mov_b32_e32 v83, v2
	v_mov_b32_e32 v84, v2
	v_mov_b32_e32 v85, v2
	v_mov_b32_e32 v86, v2
	v_mov_b32_e32 v87, v2
	v_mov_b32_e32 v88, v2
	v_mov_b32_e32 v89, v2
	v_mov_b32_e32 v90, v2
	v_mov_b32_e32 v91, v2
	v_mov_b32_e32 v92, v2
	v_mov_b32_e32 v93, v2
	v_mov_b32_e32 v94, v2
	v_mov_b32_e32 v95, v2
	v_mov_b32_e32 v96, v2
	v_mov_b32_e32 v97, v2
	v_mov_b32_e32 v98, v2
	v_mov_b32_e32 v99, v2
	v_mov_b32_e32 v100, v2
	v_mov_b32_e32 v101, v2
	v_mov_b32_e32 v102, v2
	v_mov_b32_e32 v103, v2
	v_mov_b32_e32 v104, v2
	v_mov_b32_e32 v105, v2
	v_mov_b32_e32 v106, v2
	v_mov_b32_e32 v107, v2
	v_mov_b32_e32 v108, v2
	v_mov_b32_e32 v109, v2
	v_mov_b32_e32 v110, v2
	v_mov_b32_e32 v111, v2
	v_mov_b32_e32 v112, v2
	v_mov_b32_e32 v113, v2
	v_mov_b32_e32 v114, v2
	v_mov_b32_e32 v115, v2
	v_mov_b32_e32 v116, v2
	v_mov_b32_e32 v117, v2
	v_mov_b32_e32 v118, v2
	v_mov_b32_e32 v119, v2
	v_mov_b32_e32 v120, v2
	v_mov_b32_e32 v121, v2
	v_mov_b32_e32 v122, v2
	v_mov_b32_e32 v123, v2
	v_mov_b32_e32 v124, v2
	v_mov_b32_e32 v125, v2
	v_mov_b32_e32 v126, v2
	v_mov_b32_e32 v127, v2
	v_mov_b32_e32 v128, v2
	v_mov_b32_e32 v129, v2

.LBB0_809:
	s_or_b64 exec, exec, s[18:19]
	v_mad_u64_u32 v[2:3], s[18:19], v149, s52, 0
	v_mad_u64_u32 v[98:99], s[18:19], v119, s52, 0
	v_mad_u64_u32 v[96:97], s[18:19], v150, s52, 0
	v_mad_u64_u32 v[94:95], s[18:19], v151, s52, 0
	v_mad_u64_u32 v[92:93], s[18:19], v152, s52, 0
	s_mov_b32 s18, s98
	s_mul_hi_u32 s35, s18, 0x55555556
	s_mul_i32 s18, s35, 3
	s_sub_i32 s34, s98, s18
	s_add_u32 s12, s46, s12
	v_mov_b32_e32 v101, v0
	s_addc_u32 s13, s48, s13
	s_waitcnt lgkmcnt(0)
	s_barrier
	v_mad_i64_i32 v[92:93], s[18:19], s34, v169, v[92:93]
	v_mov_b32_e32 v119, v0
	v_mad_i64_i32 v[94:95], s[18:19], s34, v169, v[94:95]
	v_mad_i64_i32 v[96:97], s[18:19], s34, v169, v[96:97]
	v_mad_i64_i32 v[98:99], s[18:19], s34, v169, v[98:99]
	v_lshl_add_u64 v[100:101], s[12:13], 0, v[100:101]
	v_mad_u64_u32 v[2:3], s[12:13], s35, v170, v[2:3]
	v_lshl_add_u64 v[92:93], v[92:93], 0, v[118:119]
	v_lshl_add_u64 v[94:95], v[94:95], 0, v[118:119]
	v_lshl_add_u64 v[96:97], v[96:97], 0, v[118:119]
	v_lshl_add_u64 v[98:99], v[98:99], 0, v[118:119]
	v_lshl_add_u64 v[2:3], v[2:3], 0, v[118:119]
	v_lshl_add_u64 v[92:93], s[16:17], 0, v[92:93]
	v_lshl_add_u64 v[94:95], s[16:17], 0, v[94:95]
	v_lshl_add_u64 v[96:97], s[16:17], 0, v[96:97]
	v_lshl_add_u64 v[98:99], s[16:17], 0, v[98:99]
	s_mov_b32 s34, 1
	v_lshl_add_u64 v[102:103], v[102:103], 1, s[84:85]
	v_lshl_add_u64 v[104:105], v[104:105], 1, s[84:85]
	v_lshl_add_u64 v[106:107], v[106:107], 1, s[84:85]
	v_lshl_add_u64 v[108:109], v[108:109], 1, s[84:85]
	v_lshl_add_u64 v[110:111], v[110:111], 1, s[84:85]
	v_lshl_add_u64 v[112:113], v[112:113], 1, s[84:85]
	v_lshl_add_u64 v[114:115], v[114:115], 1, s[84:85]
	v_lshl_add_u64 v[116:117], v[116:117], 1, s[84:85]
	v_lshl_add_u64 v[118:119], s[84:85], 0, v[2:3]
	s_mov_b64 s[12:13], 0
	s_branch .LBB0_812
